# v6 + P1 late p->bf16 conversion: four always-in-range iterations batched (8 loads in flight) instead of a serial load/wait/store loop
# baseline (speedup 1.0000x reference)
; __device__ __forceinline__ unsigned pk2(float lo, float hi) { f32x2_t v = {lo, hi}; bf16x2_t b = __builtin_convertvector(v, bf16x2_t); return __builtin_bit_cast(unsigned, b); }
; __device__ __forceinline__ void p0_late(const Ctx& C, LAS unsigned char* lds, int tid) {
;     ...
;     for (int idx = blockIdx.x * 512 + tid; idx < MP * 32; idx += gridDim.x * 512) {
;         const int row = idx >> 5, c8 = (idx & 31) * 8; u32x4 o = (u32x4){0u, 0u, 0u, 0u};
;         if (row < MTOK) { const float* src = row < MPROMPT ? C.pp + (size_t)row * PLE + c8 : C.ps + (size_t)(row - MPROMPT) * PLE + c8;
;             const f32x4 a = __builtin_nontemporal_load((const f32x4*)src), b = __builtin_nontemporal_load((const f32x4*)(src + 4)); o.x = pk2(a[0], a[1]); o.y = pk2(a[2], a[3]); o.z = pk2(b[0], b[1]); o.w = pk2(b[2], b[3]); }
;         __builtin_nontemporal_store(o, (u32x4*)(C.PB + (size_t)row * PLE + c8));
;     }
.LBB0_153:
	s_or_b64 exec, exec, s[4:5]
	v_lshl_add_u32 v7, s2, 9, v24
	s_cmp_lg_u32 s42, 0x100
	s_cbranch_scc1 .Lpf_skip1
	v_readlane_b32 s76, v237, 55
	v_readlane_b32 s77, v237, 56
	v_lshrrev_b32_e32 v180, 5, v7
	v_and_b32_e32 v181, 31, v7
	v_lshlrev_b32_e32 v182, 10, v180
	v_lshl_add_u32 v182, v181, 5, v182
	v_lshlrev_b32_e32 v183, 9, v180
	v_lshl_add_u32 v183, v181, 4, v183
	global_load_dwordx4 v[184:187], v182, s[68:69] nt
	global_load_dwordx4 v[188:191], v182, s[68:69] offset:16 nt
	v_add_u32_e32 v182, 0x400000, v182
	global_load_dwordx4 v[192:195], v182, s[68:69] nt
	global_load_dwordx4 v[196:199], v182, s[68:69] offset:16 nt
	v_add_u32_e32 v182, 0x400000, v182
	global_load_dwordx4 v[200:203], v182, s[68:69] nt
	global_load_dwordx4 v[204:207], v182, s[68:69] offset:16 nt
	v_add_u32_e32 v182, 0x400000, v182
	global_load_dwordx4 v[208:211], v182, s[68:69] nt
	global_load_dwordx4 v[212:215], v182, s[68:69] offset:16 nt
	s_waitcnt vmcnt(6)
	v_cvt_pk_bf16_f32 v184, v184, v185
	v_cvt_pk_bf16_f32 v185, v186, v187
	v_cvt_pk_bf16_f32 v186, v188, v189
	v_cvt_pk_bf16_f32 v187, v190, v191
	global_store_dwordx4 v183, v[184:187], s[76:77] nt
	s_nop 1
	v_add_u32_e32 v183, 0x200000, v183
	s_waitcnt vmcnt(5)
	v_cvt_pk_bf16_f32 v192, v192, v193
	v_cvt_pk_bf16_f32 v193, v194, v195
	v_cvt_pk_bf16_f32 v194, v196, v197
	v_cvt_pk_bf16_f32 v195, v198, v199
	global_store_dwordx4 v183, v[192:195], s[76:77] nt
	s_nop 1
	v_add_u32_e32 v183, 0x200000, v183
	s_waitcnt vmcnt(4)
	v_cvt_pk_bf16_f32 v200, v200, v201
	v_cvt_pk_bf16_f32 v201, v202, v203
	v_cvt_pk_bf16_f32 v202, v204, v205
	v_cvt_pk_bf16_f32 v203, v206, v207
	global_store_dwordx4 v183, v[200:203], s[76:77] nt
	s_nop 1
	v_add_u32_e32 v183, 0x200000, v183
	s_waitcnt vmcnt(3)
	v_cvt_pk_bf16_f32 v208, v208, v209
	v_cvt_pk_bf16_f32 v209, v210, v211
	v_cvt_pk_bf16_f32 v210, v212, v213
	v_cvt_pk_bf16_f32 v211, v214, v215
	global_store_dwordx4 v183, v[208:211], s[76:77] nt
	v_add_u32_e32 v7, 0x80000, v7
.Lpf_skip1:
	s_mov_b32 s0, 0x82000
	v_cmp_gt_i32_e32 vcc, s0, v7
	s_and_saveexec_b64 s[0:1], vcc
	s_cbranch_execz .LBB0_160
	s_lshl_b32 s3, s42, 9
	v_lshl_add_u32 v10, s2, 12, v1
	s_lshl_b32 s10, s42, 12
	s_mov_b64 s[4:5], 0
	v_mov_b32_e32 v5, 0
	s_mov_b32 s11, 0x81fff
	s_branch .LBB0_156

; __device__ __forceinline__ unsigned pk2(float lo, float hi) { f32x2_t v = {lo, hi}; bf16x2_t b = __builtin_convertvector(v, bf16x2_t); return __builtin_bit_cast(unsigned, b); }
; __device__ __forceinline__ void p0_late(const Ctx& C, LAS unsigned char* lds, int tid) {
;     ...
;     for (int idx = blockIdx.x * 512 + tid; idx < MP * 32; idx += gridDim.x * 512) {
;         const int row = idx >> 5, c8 = (idx & 31) * 8; u32x4 o = (u32x4){0u, 0u, 0u, 0u};
;         if (row < MTOK) { const float* src = row < MPROMPT ? C.pp + (size_t)row * PLE + c8 : C.ps + (size_t)(row - MPROMPT) * PLE + c8;
;             const f32x4 a = __builtin_nontemporal_load((const f32x4*)src), b = __builtin_nontemporal_load((const f32x4*)(src + 4)); o.x = pk2(a[0], a[1]); o.y = pk2(a[2], a[3]); o.z = pk2(b[0], b[1]); o.w = pk2(b[2], b[3]); }
;         __builtin_nontemporal_store(o, (u32x4*)(C.PB + (size_t)row * PLE + c8));
;     }
.Lpf_skip0:
	s_mov_b32 s0, 0x82000
	v_cmp_gt_i32_e32 vcc, s0, v7
	s_and_saveexec_b64 s[0:1], vcc
	s_cbranch_execz .LBB0_246
	s_lshl_b32 s3, s42, 9
	v_lshl_add_u32 v10, s2, 12, v1
	s_lshl_b32 s10, s42, 12
	s_mov_b64 s[4:5], 0
	s_movk_i32 s11, 0x407f
	v_mov_b32_e32 v5, 0
	s_movk_i32 s12, 0x4000
	s_mov_b32 s13, 0x81fff
	s_branch .LBB0_242
